# grid barrier: every waiter polls the TOP arrival counter (target (gen+1)*nx) instead of generation words: two release hops removed
# speedup vs baseline: 1.0047x; 1.0001x over previous
.LBB0_46:
	s_or_b64 exec, exec, s[2:3]
	v_cvt_f32_u32_e32 v4, v2
	s_waitcnt vmcnt(0)
	v_readfirstlane_b32 s2, v3
	v_sub_u32_e32 v3, 0, v2
	v_rcp_iflag_f32_e32 v4, v4
	v_add_u32_e32 v5, s2, v1
	v_mul_f32_e32 v4, 0x4f7ffffe, v4
	v_cvt_u32_f32_e32 v4, v4
	v_mul_lo_u32 v1, v3, v4
	v_mul_hi_u32 v1, v4, v1
	v_add_u32_e32 v1, v4, v1
	v_mul_hi_u32 v1, v5, v1
	v_mul_lo_u32 v3, v1, v2
	v_sub_u32_e32 v3, v5, v3
	v_add_u32_e32 v4, 1, v1
	v_cmp_ge_u32_e32 vcc, v3, v2
	s_nop 1
	v_cndmask_b32_e32 v1, v1, v4, vcc
	v_sub_u32_e32 v4, v3, v2
	v_cndmask_b32_e32 v3, v3, v4, vcc
	v_add_u32_e32 v4, 1, v1
	v_cmp_ge_u32_e32 vcc, v3, v2
	v_add_u32_e32 v3, 1, v5
	s_nop 0
	v_cndmask_b32_e32 v1, v1, v4, vcc
	v_mul_lo_u32 v4, v2, v1
	v_add_u32_e32 v2, v4, v2
	v_cmp_ne_u32_e32 vcc, v3, v2
	s_and_saveexec_b64 s[2:3], vcc
	s_xor_b64 s[10:11], exec, s[2:3]
	s_cbranch_execz .LBB0_60
	s_waitcnt lgkmcnt(0)
	v_add_u32_e32 v2, 1, v1
	v_mul_lo_u32 v2, v2, v0
	s_add_u32 s20, s6, 0x7400
	s_addc_u32 s21, s7, 0
	global_load_dword v0, v113, s[20:21] sc1
	s_waitcnt vmcnt(0)
	v_cmp_lt_u32_e32 vcc, v0, v2
	s_and_saveexec_b64 s[12:13], vcc
	s_cbranch_execz .LBB0_59
	s_add_u32 s16, s6, 0x4200
	s_addc_u32 s17, s7, 0
	s_mov_b32 s2, 1
	s_mov_b64 s[22:23], 0
	s_branch .LBB0_50

.LBB0_52:
	global_load_dword v0, v113, s[20:21] sc1
	s_add_i32 s2, s2, 1
	s_mov_b64 s[28:29], -1
	s_waitcnt vmcnt(0)
	v_cmp_ge_u32_e32 vcc, v0, v2
	s_orn2_b64 s[26:27], vcc, exec
	s_branch .LBB0_49

.LBB0_63:
	s_or_b64 exec, exec, s[10:11]
	v_cvt_f32_u32_e32 v3, v0
	s_waitcnt vmcnt(0)
	v_readfirstlane_b32 s2, v2
	s_add_u32 s10, s6, 0x7500
	s_addc_u32 s11, s7, 0
	v_rcp_iflag_f32_e32 v3, v3
	v_add_u32_e32 v1, s2, v1
	v_add_u32_e32 v4, 1, v1
	s_mov_b64 s[16:17], -1
	v_mul_f32_e32 v2, 0x4f7ffffe, v3
	v_cvt_u32_f32_e32 v2, v2
	v_sub_u32_e32 v3, 0, v0
	v_mul_lo_u32 v3, v3, v2
	v_mul_hi_u32 v3, v2, v3
	v_add_u32_e32 v2, v2, v3
	v_mul_hi_u32 v2, v1, v2
	v_mul_lo_u32 v3, v2, v0
	v_sub_u32_e32 v1, v1, v3
	v_add_u32_e32 v5, 1, v2
	v_cmp_ge_u32_e32 vcc, v1, v0
	v_sub_u32_e32 v3, v1, v0
	s_nop 0
	v_cndmask_b32_e32 v2, v2, v5, vcc
	v_cndmask_b32_e32 v1, v1, v3, vcc
	v_add_u32_e32 v3, 1, v2
	v_cmp_ge_u32_e32 vcc, v1, v0
	s_nop 1
	v_cndmask_b32_e32 v2, v2, v3, vcc
	v_mul_lo_u32 v1, v0, v2
	v_add_u32_e32 v0, v1, v0
	v_cmp_ne_u32_e32 vcc, v4, v0
	v_mov_b32_e32 v5, v0
	v_mov_b64_e32 v[0:1], s[10:11]
	s_and_saveexec_b64 s[12:13], vcc
	s_cbranch_execz .LBB0_75
	s_sub_u32 s10, s10, 0x100
	s_subb_u32 s11, s11, 0
	global_load_dword v0, v113, s[10:11] sc1
	s_mov_b64 s[22:23], 0
	s_waitcnt vmcnt(0)
	v_cmp_lt_u32_e32 vcc, v0, v5
	s_and_saveexec_b64 s[20:21], vcc
	s_cbranch_execz .LBB0_74
	s_add_u32 s16, s6, 0x4200
	s_addc_u32 s17, s7, 0
	s_mov_b32 s2, 1
	s_mov_b64 s[6:7], 0
	s_branch .LBB0_67

.LBB0_69:
	global_load_dword v0, v113, s[10:11] sc1
	s_add_i32 s2, s2, 1
	s_mov_b64 s[26:27], -1
	s_waitcnt vmcnt(0)
	v_cmp_ge_u32_e32 vcc, v0, v5
	s_orn2_b64 s[24:25], vcc, exec
	s_branch .LBB0_66
